# non-temporal (nt) cache policy on read-once input streams: phase-0 x / weight loads and the mixout residual x loads, so they stop evicting the bf16 operands the next GEMM needs
# speedup vs baseline: 1.0538x; 1.0146x over previous
; __device__ void phase_convert(const Params& p, u16* smem) {
;     ...
;     const long n4x = (long)SEQ * DM / 4, n4m = (long)MEML * DM / 4;
;     for (long i = (long)bid * 256 + t; i < n4x + n4m; i += (long)nb * 256) {
;       const float* s; u16* d; long j;
;       if (i < n4x) { s = p.x; d = p.xb(); j = i; } else { s = p.mem; d = p.memb(); j = i - n4x; }
;       float4 v = *(const float4*)(s + j * 4);
;       store_bf4(d + j * 4, v.x, v.y, v.z, v.w);
;     }
.LBB0_28:
	v_cmp_gt_i64_e32 vcc, s[10:11], v[4:5]
	v_lshl_add_u64 v[14:15], v[6:7], 0, s[12:13]
	v_lshl_add_u64 v[4:5], v[4:5], 0, s[4:5]
	v_cndmask_b32_e32 v17, v9, v10, vcc
	v_cndmask_b32_e32 v16, v11, v12, vcc
	v_cndmask_b32_e32 v19, v15, v7, vcc
	v_cndmask_b32_e32 v18, v14, v6, vcc
	v_lshl_add_u64 v[14:15], v[18:19], 2, v[16:17]
	global_load_dwordx4 v[14:17], v[14:15], off nt
	v_cndmask_b32_e32 v2, v1, v8, vcc
	v_lshl_add_u64 v[20:21], s[92:93], 0, v[2:3]
	v_cmp_lt_i64_e32 vcc, s[14:15], v[4:5]
	v_lshl_add_u64 v[6:7], v[6:7], 0, s[6:7]
	v_lshl_add_u64 v[18:19], v[18:19], 1, v[20:21]
	s_or_b64 s[8:9], vcc, s[8:9]
	s_waitcnt vmcnt(0)
	v_cvt_pk_bf16_f32 v14, v14, v15
	v_cvt_pk_bf16_f32 v15, v16, v17
	global_store_dwordx2 v[18:19], v[14:15], off
	s_andn2_b64 exec, exec, s[8:9]
	s_cbranch_execnz .LBB0_28

; __device__ __forceinline__ u16 f2bf(float f) { return (u16)(pack2(f, f) & 0xffffu); }
; __device__ __forceinline__ void transpose_tile(const float* __restrict__ src, u16* __restrict__ dst, int R, int C, int tr, int tc, u16* lds) {
;   const int t = threadIdx.x;
; #pragma unroll
;   for (int i = 0; i < 4; i++) {
;     int r = (t >> 4) + 16 * i, c4 = (t & 15) * 4;
;     float4 v = *(const float4*)(src + (long)(tr * 64 + r) * C + tc * 64 + c4);
;     lds[(c4 + 0) * 66 + r] = f2bf(v.x);
;     lds[(c4 + 1) * 66 + r] = f2bf(v.y);
;     lds[(c4 + 2) * 66 + r] = f2bf(v.z);
;     lds[(c4 + 3) * 66 + r] = f2bf(v.w);
;   }
;   __syncthreads();
;   {
;     int n = t >> 2, k0 = (t & 3) * 16;
;     const uint32_t* s32 = (const uint32_t*)(lds + n * 66 + k0);
;     uint4 a, b;
;     a.x = s32[0]; a.y = s32[1]; a.z = s32[2]; a.w = s32[3];
;     b.x = s32[4]; b.y = s32[5]; b.z = s32[6]; b.w = s32[7];
;     u16* d = dst + (long)(tc * 64 + n) * R + tr * 64 + k0;
;     *(uint4*)d = a;
;     *(uint4*)(d + 8) = b;
;   }
;   __syncthreads();
; __device__ void phase_convert(const Params& p, u16* smem) {
;     ...
;   for (int j = bid; j < total; j += nb) {
;     const float* src; u16* dst; int R, C, tl;
;     if (j < T_IN) { src = p.w_in; dst = p.WinT(); R = DM; C = INW; tl = j; }
;     else {
;       int q = (j - T_IN) / T_SQ; tl = (j - T_IN) % T_SQ; R = DM; C = DM;
;       src = q == 0 ? p.w_mix_out : q == 1 ? p.mem_w_q : q == 2 ? p.mem_w_k : q == 3 ? p.mem_w_v : p.mem_w_o;
;       dst = q == 0 ? p.WmixT() : q == 1 ? p.WqT() : q == 2 ? p.WkT() : q == 3 ? p.WvT() : p.WoT();
;     }
;     int ntc = C / 64;
;     transpose_tile(src, dst, R, C, tl / ntc, tl % ntc, smem);
.LBB0_32:
	s_lshr_b32 s16, s2, 6
	v_cvt_f32_ubyte0_e32 v11, s16
	v_rcp_iflag_f32_e32 v11, v11
	s_sub_i32 s19, 0, s16
	s_abs_i32 s18, s3
	s_ashr_i32 s17, s3, 31
	v_mul_f32_e32 v11, 0x4f7ffffe, v11
	v_cvt_u32_f32_e32 v11, v11
	s_nop 0
	v_readfirstlane_b32 s21, v11
	s_mul_i32 s19, s19, s21
	s_mul_hi_u32 s19, s21, s19
	s_add_i32 s21, s21, s19
	s_mul_hi_u32 s19, s18, s21
	s_mul_i32 s21, s19, s16
	s_sub_i32 s18, s18, s21
	s_add_i32 s22, s19, 1
	s_sub_i32 s21, s18, s16
	s_cmp_ge_u32 s18, s16
	s_cselect_b32 s19, s22, s19
	s_cselect_b32 s18, s21, s18
	s_add_i32 s21, s19, 1
	s_cmp_ge_u32 s18, s16
	s_cselect_b32 s18, s21, s19
	s_xor_b32 s18, s18, s17
	s_sub_i32 s17, s18, s17
	s_mul_i32 s18, s17, s16
	s_sub_i32 s3, s3, s18
	s_lshl_b32 s18, s3, 6
	s_ashr_i32 s19, s18, 31
	s_lshl_b32 s16, s17, 6
	s_lshl_b64 s[22:23], s[18:19], 2
	s_add_u32 s12, s12, s22
	s_addc_u32 s13, s13, s23
	v_or_b32_e32 v11, s16, v133
	v_lshl_add_u64 v[24:25], s[12:13], 0, v[2:3]
	v_mad_i64_i32 v[12:13], s[12:13], v11, s2, 0
	v_add_u32_e32 v11, s16, v7
	v_mad_i64_i32 v[16:17], s[12:13], v11, s2, 0
	v_add_u32_e32 v11, s16, v8
	v_mad_i64_i32 v[20:21], s[12:13], v11, s2, 0
	v_add_u32_e32 v11, s16, v9
	v_lshl_add_u64 v[12:13], v[12:13], 2, v[24:25]
	v_lshl_add_u64 v[16:17], v[16:17], 2, v[24:25]
	v_lshl_add_u64 v[20:21], v[20:21], 2, v[24:25]
	v_mad_i64_i32 v[26:27], s[2:3], v11, s2, 0
	global_load_dwordx4 v[12:15], v[12:13], off nt
	v_lshl_add_u64 v[24:25], v[26:27], 2, v[24:25]
	global_load_dwordx4 v[16:19], v[16:17], off nt
	v_add_u32_e32 v28, s18, v1
	global_load_dwordx4 v[20:23], v[20:21], off nt
	v_ashrrev_i32_e32 v29, 31, v28
	global_load_dwordx4 v[24:27], v[24:25], off nt
	v_lshlrev_b64 v[28:29], 12, v[28:29]
	v_lshl_add_u64 v[28:29], s[14:15], 0, v[28:29]
	s_ashr_i32 s17, s16, 31
	s_add_i32 s20, s20, s94
	s_cmpk_lt_i32 s20, 0x1e00
	s_waitcnt vmcnt(3)
	v_cvt_pk_bf16_f32 v11, v12, s0
	v_cvt_pk_bf16_f32 v12, v13, s0
	v_cvt_pk_bf16_f32 v13, v14, s0
	v_cvt_pk_bf16_f32 v14, v15, s0
	s_waitcnt vmcnt(2)
	v_cvt_pk_bf16_f32 v15, v16, s0
	v_cvt_pk_bf16_f32 v16, v17, s0
	v_cvt_pk_bf16_f32 v17, v18, s0
	v_cvt_pk_bf16_f32 v18, v19, s0
	s_waitcnt vmcnt(1)
	v_cvt_pk_bf16_f32 v19, v20, s0
	v_cvt_pk_bf16_f32 v20, v21, s0
	v_cvt_pk_bf16_f32 v21, v22, s0
	v_cvt_pk_bf16_f32 v22, v23, s0
	s_waitcnt vmcnt(0)
	v_cvt_pk_bf16_f32 v23, v24, s0
	v_cvt_pk_bf16_f32 v24, v25, s0
	v_cvt_pk_bf16_f32 v25, v26, s0
	v_cvt_pk_bf16_f32 v26, v27, s0
	ds_write_b16 v6, v11
	ds_write_b16 v6, v12 offset:132
	ds_write_b16 v6, v13 offset:264
	ds_write_b16 v6, v14 offset:396
	ds_write_b16 v6, v15 offset:32
	ds_write_b16 v6, v16 offset:164
	ds_write_b16 v6, v17 offset:296
	ds_write_b16 v6, v18 offset:428
	ds_write_b16 v6, v19 offset:64
	ds_write_b16 v6, v20 offset:196
	ds_write_b16 v6, v21 offset:328
	ds_write_b16 v6, v22 offset:460
	ds_write_b16 v6, v23 offset:96
	ds_write_b16 v6, v24 offset:228
	ds_write_b16 v6, v25 offset:360
	ds_write_b16 v6, v26 offset:492
	s_waitcnt lgkmcnt(0)
	s_barrier
	ds_read2_b32 v[12:13], v10 offset1:1
	ds_read2_b32 v[14:15], v10 offset0:2 offset1:3
	ds_read2_b32 v[16:17], v10 offset0:4 offset1:5
	ds_read2_b32 v[18:19], v10 offset0:6 offset1:7
	v_lshl_add_u64 v[20:21], s[16:17], 1, v[28:29]
	v_lshl_add_u64 v[20:21], v[20:21], 0, v[4:5]
	s_waitcnt lgkmcnt(2)
	global_store_dwordx4 v[20:21], v[12:15], off
	s_waitcnt lgkmcnt(0)
	global_store_dwordx4 v[20:21], v[16:19], off offset:16
	s_barrier
	s_cbranch_scc0 .LBB0_58

; __device__ __forceinline__ float bflo(uint32_t w) { return __uint_as_float(w << 16); }
; __device__ __forceinline__ float bfhi(uint32_t w) { return __uint_as_float(w & 0xffff0000u); }
; template <bool RES_BF16>
; __device__ __forceinline__ void gemm_residual(const u16* A, const u16* WT, const void* res_, float* pre, u16* smem) {
;     ...
;               [&](int j, int m, int nb, f32x4 (&a)[4]) {
;                 int mt = j % MT, nt = j / MT;
;                 const long off = (long)(mt * 128 + m) * DM + nt * 128 + nb;
; #pragma unroll
;                 for (int q = 0; q < 4; q++) {
;                   float4 xv;
;                   if (RES_BF16) {
;                     uint2 xw = *(const uint2*)((const u16*)res_ + off + q * 16);
;                     xv.x = bflo(xw.x); xv.y = bfhi(xw.x); xv.z = bflo(xw.y); xv.w = bfhi(xw.y);
;                   } else {
;                     xv = *(const float4*)((const float*)res_ + off + q * 16);
;                   }
;                   float4 r; r.x = DN_ALPHA * xv.x + a[q][0]; r.y = DN_ALPHA * xv.y + a[q][1]; r.z = DN_ALPHA * xv.z + a[q][2]; r.w = DN_ALPHA * xv.w + a[q][3];
;                   *(float4*)(pre + off + q * 16) = r;
;                 }
.LBB0_408:
	s_ashr_i32 s21, s2, 31
	s_lshr_b32 s21, s21, 26
	s_add_i32 s21, s2, s21
	s_and_b32 s24, s21, 0x1ffffc0
	s_sub_i32 s2, s2, s24
	v_lshl_add_u32 v96, s2, 7, v85
	s_lshl_b32 s2, s21, 1
	s_and_b32 s2, s2, 0xffffff80
	s_ashr_i32 s21, s2, 31
	v_ashrrev_i32_e32 v97, 31, v96
	v_mov_b32_e32 v99, s21
	v_or_b32_e32 v98, s2, v70
	v_lshlrev_b64 v[92:93], 11, v[96:97]
	v_lshl_add_u64 v[92:93], v[92:93], 0, v[98:99]
	v_lshlrev_b64 v[100:101], 2, v[92:93]
	v_lshl_add_u64 v[102:103], s[76:77], 0, v[100:101]
	global_load_dwordx4 v[92:95], v[102:103], off nt
	v_lshl_add_u64 v[100:101], s[14:15], 0, v[100:101]
	s_andn2_b64 vcc, exec, s[22:23]
	s_waitcnt vmcnt(0)
	v_pk_fma_f32 v[60:61], v[92:93], s[20:21], v[60:61] op_sel_hi:[1,0,1]
	v_pk_fma_f32 v[62:63], v[94:95], s[20:21], v[62:63] op_sel_hi:[1,0,1]
	global_store_dwordx4 v[100:101], v[60:63], off
	global_load_dwordx4 v[60:63], v[102:103], off offset:64 nt
	s_waitcnt vmcnt(0)
	v_pk_fma_f32 v[56:57], v[60:61], s[20:21], v[56:57] op_sel_hi:[1,0,1]
	v_pk_fma_f32 v[58:59], v[62:63], s[20:21], v[58:59] op_sel_hi:[1,0,1]
	global_store_dwordx4 v[100:101], v[56:59], off offset:64
	global_load_dwordx4 v[56:59], v[102:103], off offset:128 nt
	s_waitcnt vmcnt(0)
	v_pk_fma_f32 v[52:53], v[56:57], s[20:21], v[52:53] op_sel_hi:[1,0,1]
	v_pk_fma_f32 v[54:55], v[58:59], s[20:21], v[54:55] op_sel_hi:[1,0,1]
	global_store_dwordx4 v[100:101], v[52:55], off offset:128
	global_load_dwordx4 v[52:55], v[102:103], off offset:192 nt
	v_or_b32_e32 v56, 16, v96
	v_ashrrev_i32_e32 v57, 31, v56
	v_lshlrev_b64 v[56:57], 11, v[56:57]
	v_lshl_add_u64 v[56:57], v[56:57], 0, v[98:99]
	v_lshlrev_b64 v[56:57], 2, v[56:57]
	v_lshl_add_u64 v[58:59], s[76:77], 0, v[56:57]
	s_waitcnt vmcnt(0)
	v_pk_fma_f32 v[48:49], v[52:53], s[20:21], v[48:49] op_sel_hi:[1,0,1]
	v_pk_fma_f32 v[50:51], v[54:55], s[20:21], v[50:51] op_sel_hi:[1,0,1]
	global_store_dwordx4 v[100:101], v[48:51], off offset:192
	global_load_dwordx4 v[48:51], v[58:59], off nt
	v_lshl_add_u64 v[52:53], s[14:15], 0, v[56:57]
	s_waitcnt vmcnt(0)
	v_pk_fma_f32 v[44:45], v[48:49], s[20:21], v[44:45] op_sel_hi:[1,0,1]
	v_pk_fma_f32 v[46:47], v[50:51], s[20:21], v[46:47] op_sel_hi:[1,0,1]
	global_store_dwordx4 v[52:53], v[44:47], off
	global_load_dwordx4 v[44:47], v[58:59], off offset:64 nt
	s_waitcnt vmcnt(0)
	v_pk_fma_f32 v[40:41], v[44:45], s[20:21], v[40:41] op_sel_hi:[1,0,1]
	v_pk_fma_f32 v[42:43], v[46:47], s[20:21], v[42:43] op_sel_hi:[1,0,1]
	global_store_dwordx4 v[52:53], v[40:43], off offset:64
	global_load_dwordx4 v[40:43], v[58:59], off offset:128 nt
	s_waitcnt vmcnt(0)
	v_pk_fma_f32 v[36:37], v[40:41], s[20:21], v[36:37] op_sel_hi:[1,0,1]
	v_pk_fma_f32 v[38:39], v[42:43], s[20:21], v[38:39] op_sel_hi:[1,0,1]
	global_store_dwordx4 v[52:53], v[36:39], off offset:128
	global_load_dwordx4 v[36:39], v[58:59], off offset:192 nt
	v_or_b32_e32 v40, 32, v96
	v_ashrrev_i32_e32 v41, 31, v40
	v_lshlrev_b64 v[40:41], 11, v[40:41]
	v_lshl_add_u64 v[40:41], v[40:41], 0, v[98:99]
	v_lshlrev_b64 v[40:41], 2, v[40:41]
	v_lshl_add_u64 v[42:43], s[76:77], 0, v[40:41]
	s_waitcnt vmcnt(0)
	v_pk_fma_f32 v[32:33], v[36:37], s[20:21], v[32:33] op_sel_hi:[1,0,1]
	v_pk_fma_f32 v[34:35], v[38:39], s[20:21], v[34:35] op_sel_hi:[1,0,1]
	global_store_dwordx4 v[52:53], v[32:35], off offset:192
	global_load_dwordx4 v[32:35], v[42:43], off nt
	v_lshl_add_u64 v[36:37], s[14:15], 0, v[40:41]
	s_waitcnt vmcnt(0)
	v_pk_fma_f32 v[28:29], v[32:33], s[20:21], v[28:29] op_sel_hi:[1,0,1]
	v_pk_fma_f32 v[30:31], v[34:35], s[20:21], v[30:31] op_sel_hi:[1,0,1]
	global_store_dwordx4 v[36:37], v[28:31], off
	global_load_dwordx4 v[28:31], v[42:43], off offset:64 nt
	s_waitcnt vmcnt(0)
	v_pk_fma_f32 v[24:25], v[28:29], s[20:21], v[24:25] op_sel_hi:[1,0,1]
	v_pk_fma_f32 v[26:27], v[30:31], s[20:21], v[26:27] op_sel_hi:[1,0,1]
	global_store_dwordx4 v[36:37], v[24:27], off offset:64
	global_load_dwordx4 v[24:27], v[42:43], off offset:128 nt
	s_waitcnt vmcnt(0)
	v_pk_fma_f32 v[20:21], v[24:25], s[20:21], v[20:21] op_sel_hi:[1,0,1]
	v_pk_fma_f32 v[22:23], v[26:27], s[20:21], v[22:23] op_sel_hi:[1,0,1]
	global_store_dwordx4 v[36:37], v[20:23], off offset:128
	global_load_dwordx4 v[20:23], v[42:43], off offset:192 nt
	v_or_b32_e32 v24, 48, v96
	v_ashrrev_i32_e32 v25, 31, v24
	v_lshlrev_b64 v[24:25], 11, v[24:25]
	v_lshl_add_u64 v[24:25], v[24:25], 0, v[98:99]
	v_lshlrev_b64 v[24:25], 2, v[24:25]
	v_lshl_add_u64 v[26:27], s[76:77], 0, v[24:25]
	s_waitcnt vmcnt(0)
	v_pk_fma_f32 v[16:17], v[20:21], s[20:21], v[16:17] op_sel_hi:[1,0,1]
	v_pk_fma_f32 v[18:19], v[22:23], s[20:21], v[18:19] op_sel_hi:[1,0,1]
	global_store_dwordx4 v[36:37], v[16:19], off offset:192
	global_load_dwordx4 v[16:19], v[26:27], off nt
	v_lshl_add_u64 v[20:21], s[14:15], 0, v[24:25]
	s_waitcnt vmcnt(0)
	v_pk_fma_f32 v[12:13], v[16:17], s[20:21], v[12:13] op_sel_hi:[1,0,1]
	v_pk_fma_f32 v[14:15], v[18:19], s[20:21], v[14:15] op_sel_hi:[1,0,1]
	global_store_dwordx4 v[20:21], v[12:15], off
	global_load_dwordx4 v[12:15], v[26:27], off offset:64 nt
	s_waitcnt vmcnt(0)
	v_pk_fma_f32 v[8:9], v[12:13], s[20:21], v[8:9] op_sel_hi:[1,0,1]
	v_pk_fma_f32 v[10:11], v[14:15], s[20:21], v[10:11] op_sel_hi:[1,0,1]
	global_store_dwordx4 v[20:21], v[8:11], off offset:64
	global_load_dwordx4 v[8:11], v[26:27], off offset:128 nt
	s_waitcnt vmcnt(0)
	v_pk_fma_f32 v[4:5], v[8:9], s[20:21], v[4:5] op_sel_hi:[1,0,1]
	v_pk_fma_f32 v[6:7], v[10:11], s[20:21], v[6:7] op_sel_hi:[1,0,1]
	global_store_dwordx4 v[20:21], v[4:7], off offset:128
	global_load_dwordx4 v[4:7], v[26:27], off offset:192 nt
	s_waitcnt vmcnt(0)
	v_pk_fma_f32 v[0:1], v[4:5], s[20:21], v[0:1] op_sel_hi:[1,0,1]
	v_pk_fma_f32 v[2:3], v[6:7], s[20:21], v[2:3] op_sel_hi:[1,0,1]
	global_store_dwordx4 v[20:21], v[0:3], off offset:192
	s_cbranch_vccz .LBB0_413
